# attention loop VALU trimmed: max3 reduction tree, cvt_pk straight from exp outputs (no pk_mov), packed row-sum tree
# speedup vs baseline: 1.0085x; 1.0047x over previous
; #define LAS __attribute__((address_space(3)))
; #define MFMA32(a, b, c) __builtin_amdgcn_mfma_f32_32x32x16_bf16((a), (b), (c), 0, 0, 0)
; __device__ __forceinline__ void attn_item(const bf16_t* __restrict__ Q, const bf16_t* __restrict__ Kb, const bf16_t* __restrict__ VT, const bf16_t* __restrict__ GA, ...
;     ...
;         for (int d0 = 1; d0 < 4; ++d0) {
;             const bf16x8 k0 = *(const LAS bf16x8*)(kfp + d0 * 32), k1 = *(const LAS bf16x8*)(kfp + 32 * ATP + d0 * 32);
;             s0 = MFMA32(k0, qf[d0], s0); s1 = MFMA32(k1, qf[d0], s1);
;         }
;         float tmax = fmaxf(s0[0], s1[0]);
; #pragma unroll
;         for (int i = 1; i < 16; ++i) tmax = fmaxf(tmax, fmaxf(s0[i], s1[i]));
;         tmax = fmaxf(tmax, __shfl_xor(tmax, 32));
;         if (j == jmin || __any(tmax > ATT_THR)) {
;             const float dl = (j == jmin) ? tmax : fmaxf(tmax, 0.f);
;             mref += dl;
;             const float alpha = (j == jmin) ? 1.f : __builtin_amdgcn_exp2f(-dl);
;             lrun *= alpha;
; #pragma unroll
;             for (int i = 0; i < 16; ++i) { s0[i] -= dl; s1[i] -= dl; o0[i] *= alpha; o1[i] *= alpha; cinit[i] = cfar - mref; }
.Latt0_qkrest:
	s_waitcnt lgkmcnt(5)
	v_mfma_f32_32x32x16_bf16 v[50:65], v[198:201], v[86:89], v[50:65]
	s_waitcnt lgkmcnt(4)
	v_mfma_f32_32x32x16_bf16 v[66:81], v[202:205], v[86:89], v[66:81]
	s_waitcnt lgkmcnt(3)
	v_mfma_f32_32x32x16_bf16 v[50:65], v[206:209], v[90:93], v[50:65]
	s_waitcnt lgkmcnt(2)
	v_mfma_f32_32x32x16_bf16 v[66:81], v[210:213], v[90:93], v[66:81]
	s_waitcnt lgkmcnt(1)
	v_mfma_f32_32x32x16_bf16 v[66:81], v[218:221], v[94:97], v[66:81]
	s_waitcnt lgkmcnt(0)
	v_mfma_f32_32x32x16_bf16 v[50:65], v[222:225], v[94:97], v[50:65]
	s_nop 9
	v_max3_f32 v189, v66, v67, v68
	v_max3_f32 v190, v69, v70, v71
	v_max3_f32 v191, v72, v73, v74
	v_max3_f32 v192, v75, v76, v77
	v_max3_f32 v193, v78, v79, v80
	v_max3_f32 v194, v81, v50, v51
	v_max3_f32 v195, v52, v53, v54
	v_max3_f32 v196, v55, v56, v57
	v_max3_f32 v197, v58, v59, v60
	v_max3_f32 v198, v61, v62, v63
	v_max3_f32 v199, v64, v65, v189
	v_max3_f32 v190, v190, v191, v192
	v_max3_f32 v193, v193, v194, v195
	v_max3_f32 v196, v196, v197, v198
	v_max3_f32 v189, v199, v190, v193
	v_max_f32_e32 v189, v189, v196
	ds_bpermute_b32 v190, v1, v189
	s_waitcnt lgkmcnt(0)
	v_max_f32_e32 v190, v190, v190
	v_max_f32_e32 v189, v189, v190
	v_cmp_lt_f32_e32 vcc, s94, v189
	s_cbranch_vccz .LBB0_261
	v_max_f32_e32 v34, v189, v189
	v_max_f32_e32 v36, 0, v34
	v_exp_f32_e64 v38, -v36
	v_add_f32_e32 v132, v132, v36
	v_sub_f32_e32 v34, v0, v132
	v_pk_add_f32 v[50:51], v[50:51], v[36:37] op_sel_hi:[1,0] neg_lo:[0,1] neg_hi:[0,1]
	v_pk_add_f32 v[66:67], v[66:67], v[36:37] op_sel_hi:[1,0] neg_lo:[0,1] neg_hi:[0,1]
	v_pk_add_f32 v[52:53], v[52:53], v[36:37] op_sel_hi:[1,0] neg_lo:[0,1] neg_hi:[0,1]
	v_pk_add_f32 v[68:69], v[68:69], v[36:37] op_sel_hi:[1,0] neg_lo:[0,1] neg_hi:[0,1]
	v_pk_add_f32 v[54:55], v[54:55], v[36:37] op_sel_hi:[1,0] neg_lo:[0,1] neg_hi:[0,1]
	v_pk_add_f32 v[70:71], v[70:71], v[36:37] op_sel_hi:[1,0] neg_lo:[0,1] neg_hi:[0,1]
	v_pk_add_f32 v[56:57], v[56:57], v[36:37] op_sel_hi:[1,0] neg_lo:[0,1] neg_hi:[0,1]
	v_pk_add_f32 v[72:73], v[72:73], v[36:37] op_sel_hi:[1,0] neg_lo:[0,1] neg_hi:[0,1]
	v_pk_add_f32 v[58:59], v[58:59], v[36:37] op_sel_hi:[1,0] neg_lo:[0,1] neg_hi:[0,1]
	v_pk_add_f32 v[74:75], v[74:75], v[36:37] op_sel_hi:[1,0] neg_lo:[0,1] neg_hi:[0,1]
	v_pk_add_f32 v[60:61], v[60:61], v[36:37] op_sel_hi:[1,0] neg_lo:[0,1] neg_hi:[0,1]
	v_pk_add_f32 v[76:77], v[76:77], v[36:37] op_sel_hi:[1,0] neg_lo:[0,1] neg_hi:[0,1]
	v_pk_add_f32 v[62:63], v[62:63], v[36:37] op_sel_hi:[1,0] neg_lo:[0,1] neg_hi:[0,1]
	v_pk_add_f32 v[78:79], v[78:79], v[36:37] op_sel_hi:[1,0] neg_lo:[0,1] neg_hi:[0,1]
	v_pk_add_f32 v[64:65], v[64:65], v[36:37] op_sel_hi:[1,0] neg_lo:[0,1] neg_hi:[0,1]
	v_pk_add_f32 v[80:81], v[80:81], v[36:37] op_sel_hi:[1,0] neg_lo:[0,1] neg_hi:[0,1]
	v_pk_mul_f32 v[16:17], v[16:17], v[38:39] op_sel_hi:[1,0]
	v_pk_mul_f32 v[14:15], v[14:15], v[38:39] op_sel_hi:[1,0]
	v_pk_mul_f32 v[12:13], v[12:13], v[38:39] op_sel_hi:[1,0]
	v_pk_mul_f32 v[10:11], v[10:11], v[38:39] op_sel_hi:[1,0]
	v_pk_mul_f32 v[8:9], v[8:9], v[38:39] op_sel_hi:[1,0]
	v_pk_mul_f32 v[6:7], v[6:7], v[38:39] op_sel_hi:[1,0]
	v_pk_mul_f32 v[4:5], v[4:5], v[38:39] op_sel_hi:[1,0]
	v_pk_mul_f32 v[2:3], v[2:3], v[38:39] op_sel_hi:[1,0]
	v_pk_mul_f32 v[32:33], v[32:33], v[38:39] op_sel_hi:[1,0]
	v_pk_mul_f32 v[30:31], v[30:31], v[38:39] op_sel_hi:[1,0]
	v_pk_mul_f32 v[28:29], v[28:29], v[38:39] op_sel_hi:[1,0]
	v_pk_mul_f32 v[26:27], v[26:27], v[38:39] op_sel_hi:[1,0]
	v_pk_mul_f32 v[24:25], v[24:25], v[38:39] op_sel_hi:[1,0]
	v_pk_mul_f32 v[22:23], v[22:23], v[38:39] op_sel_hi:[1,0]
	v_pk_mul_f32 v[20:21], v[20:21], v[38:39] op_sel_hi:[1,0]
	v_pk_mul_f32 v[18:19], v[18:19], v[38:39] op_sel_hi:[1,0]
	v_mul_f32_e32 v187, v187, v38
	v_mov_b32_e32 v35, v34
	v_mov_b32_e32 v36, v34
	v_mov_b32_e32 v37, v34
	v_mov_b32_e32 v38, v34
	v_mov_b32_e32 v39, v34
	v_mov_b32_e32 v40, v34
	v_mov_b32_e32 v41, v34
	v_mov_b32_e32 v42, v34
	v_mov_b32_e32 v43, v34
	v_mov_b32_e32 v44, v34
	v_mov_b32_e32 v45, v34
	v_mov_b32_e32 v46, v34
	v_mov_b32_e32 v47, v34
	v_mov_b32_e32 v48, v34
	v_mov_b32_e32 v49, v34
; #define LAS __attribute__((address_space(3)))
; __device__ __forceinline__ unsigned pk2(float lo, float hi) { f32x2 v = {lo, hi}; bf16x2_t b = __builtin_convertvector(v, bf16x2_t); return __builtin_bit_cast(unsigned, b); }
; #define MFMA32(a, b, c) __builtin_amdgcn_mfma_f32_32x32x16_bf16((a), (b), (c), 0, 0, 0)
; #define ATT_BAR() asm volatile("s_waitcnt lgkmcnt(0)\n\ts_barrier" ::: "memory")
; __device__ __forceinline__ void attn_item(const bf16_t* __restrict__ Q, const bf16_t* __restrict__ Kb, const bf16_t* __restrict__ VT, const bf16_t* __restrict__ GA, ...
;     ...
;         float ls = 0.f;
; #pragma unroll
;         for (int i = 0; i < 16; ++i) { s0[i] = __builtin_amdgcn_exp2f(s0[i]); s1[i] = __builtin_amdgcn_exp2f(s1[i]); ls += s0[i] + s1[i]; }
;         lrun += ls;
; #pragma unroll
;         for (int s = 0; s < 2; ++s) {
;             u32x4 pa, pb;
;             pa.x = pk2(s0[8 * s + 0], s0[8 * s + 1]); pa.y = pk2(s0[8 * s + 2], s0[8 * s + 3]); pa.z = pk2(s0[8 * s + 4], s0[8 * s + 5]); pa.w = pk2(s0[8 * s + 6], s0[8 * s + 7]);
;             pb.x = pk2(s1[8 * s + 0], s1[8 * s + 1]); pb.y = pk2(s1[8 * s + 2], s1[8 * s + 3]); pb.z = pk2(s1[8 * s + 4], s1[8 * s + 5]); pb.w = pk2(s1[8 * s + 6], s1[8 * s + 7]);
;             const bf16x8 va0 = *(const LAS bf16x8*)(vfp + 32 * s), va1 = *(const LAS bf16x8*)(vfp + 32 * ATP + 32 * s);
;             const bf16x8 vb0 = *(const LAS bf16x8*)(vfp + 64 + 32 * s), vb1 = *(const LAS bf16x8*)(vfp + 32 * ATP + 64 + 32 * s);
;             o0 = MFMA32(va0, __builtin_bit_cast(bf16x8, pa), o0); o1 = MFMA32(va1, __builtin_bit_cast(bf16x8, pa), o1);
;             o0 = MFMA32(vb0, __builtin_bit_cast(bf16x8, pb), o0); o1 = MFMA32(vb1, __builtin_bit_cast(bf16x8, pb), o1);
;         }
;         buf ^= 1;
; #pragma unroll
;         for (int i = 0; i < 8; ++i) *(LAS u32x4*)(pl + buf * ATT_WAVE_LDS + stoff + 8 * i * ATP) = tr[i];
;         tg += (j + 2 <= 8) ? tstep : (size_t)0;
; #pragma unroll
;         for (int i = 0; i < 8; ++i) tr[i] = *(const u32x4*)(tg + i * rstep);
;         ATT_BAR();
.LBB0_261:
	v_add3_u32 v190, s28, v165, v167
	s_xor_b32 s72, s72, 1
	s_mul_i32 s99, s72, 0x4800
	v_add_u32_e32 v226, s99, v186
	v_exp_f32_e32 v189, v50
	v_exp_f32_e32 v220, v51
	v_exp_f32_e32 v222, v52
	v_exp_f32_e32 v224, v53
	ds_read_b128 v[50:53], v190 offset:9216
	s_waitcnt vmcnt(1)
	ds_write_b128 v226, v[126:129]
	ds_write_b128 v226, v[122:125] offset:1152
	ds_write_b128 v226, v[106:109] offset:2304
	ds_write_b128 v226, v[118:121] offset:3456
	ds_write_b128 v226, v[102:105] offset:4608
	ds_write_b128 v226, v[114:117] offset:5760
	ds_write_b128 v226, v[98:101] offset:6912
	s_waitcnt vmcnt(0)
	ds_write_b128 v226, v[110:113] offset:8064
	v_exp_f32_e32 v195, v54
	v_exp_f32_e32 v194, v55
	v_exp_f32_e32 v199, v56
	v_exp_f32_e32 v198, v57
	v_exp_f32_e32 v203, v58
	v_exp_f32_e32 v202, v59
	v_cvt_pk_bf16_f32 v54, v189, v220
	v_cvt_pk_bf16_f32 v55, v222, v224
	v_cvt_pk_bf16_f32 v56, v195, v194
	v_cvt_pk_bf16_f32 v57, v199, v198
	v_exp_f32_e32 v197, v70
	v_exp_f32_e32 v196, v71
	s_waitcnt lgkmcnt(8)
	v_mfma_f32_32x32x16_bf16 v[2:17], v[50:53], v[54:57], v[2:17]
	v_exp_f32_e32 v201, v72
	v_exp_f32_e32 v200, v73
	v_exp_f32_e32 v216, v66
	v_exp_f32_e32 v221, v67
	v_exp_f32_e32 v223, v68
	v_exp_f32_e32 v225, v69
	v_exp_f32_e32 v207, v60
	v_exp_f32_e32 v206, v61
	v_exp_f32_e32 v211, v62
	v_exp_f32_e32 v210, v63
	v_exp_f32_e32 v215, v64
	v_exp_f32_e32 v214, v65
	ds_read_b128 v[58:61], v190 offset:9280
	ds_read_b128 v[62:65], v190 offset:9248
	v_cvt_pk_bf16_f32 v50, v216, v221
	v_cvt_pk_bf16_f32 v51, v223, v225
	v_cvt_pk_bf16_f32 v52, v197, v196
	v_cvt_pk_bf16_f32 v53, v201, v200
	ds_read_b128 v[66:69], v190 offset:9312
	s_waitcnt lgkmcnt(2)
	v_mfma_f32_32x32x16_bf16 v[2:17], v[58:61], v[50:53], v[2:17]
	v_cvt_pk_bf16_f32 v58, v203, v202
	v_cvt_pk_bf16_f32 v59, v207, v206
	v_exp_f32_e32 v205, v74
	v_cvt_pk_bf16_f32 v60, v211, v210
	v_cvt_pk_bf16_f32 v61, v215, v214
	v_exp_f32_e32 v204, v75
	v_exp_f32_e32 v209, v76
	s_waitcnt lgkmcnt(1)
	v_mfma_f32_32x32x16_bf16 v[2:17], v[62:65], v[58:61], v[2:17]
	v_exp_f32_e32 v208, v77
	v_exp_f32_e32 v213, v78
	v_exp_f32_e32 v212, v79
	v_exp_f32_e32 v219, v80
	v_exp_f32_e32 v218, v81
	s_add_i32 s70, s33, 1
	v_cvt_pk_bf16_f32 v70, v205, v204
	v_cvt_pk_bf16_f32 v71, v209, v208
	v_cvt_pk_bf16_f32 v72, v213, v212
	v_cvt_pk_bf16_f32 v73, v219, v218
	s_cmp_lt_i32 s33, 6
	s_waitcnt lgkmcnt(0)
	v_mfma_f32_32x32x16_bf16 v[2:17], v[66:69], v[70:73], v[2:17]
	s_cselect_b32 s7, s64, 0
	s_lshl_b32 s28, s7, 1
	v_lshl_add_u64 v[152:153], v[152:153], 0, s[28:29]
	s_mov_b32 s67, s29
	ds_read_b128 v[62:65], v190 offset:13824
	ds_read_b128 v[74:77], v190 offset:13856
	ds_read_b128 v[78:81], v190 offset:13888
	ds_read_b128 v[190:193], v190 offset:13920
	v_lshl_add_u64 v[66:67], v[152:153], 0, s[66:67]
	v_lshl_add_u64 v[68:69], v[66:67], 0, s[68:69]
	global_load_dwordx4 v[122:125], v[66:67], off
	global_load_dwordx4 v[106:109], v[68:69], off
	v_lshl_add_u64 v[66:67], v[68:69], 0, s[68:69]
	v_lshl_add_u64 v[68:69], v[66:67], 0, s[68:69]
	global_load_dwordx4 v[118:121], v[66:67], off
	global_load_dwordx4 v[102:105], v[68:69], off
	v_lshl_add_u64 v[66:67], v[68:69], 0, s[68:69]
	v_lshl_add_u64 v[68:69], v[66:67], 0, s[68:69]
	global_load_dwordx4 v[114:117], v[66:67], off
	global_load_dwordx4 v[98:101], v[68:69], off
	v_lshl_add_u64 v[66:67], v[68:69], 0, s[68:69]
	global_load_dwordx4 v[126:129], v[152:153], off
	global_load_dwordx4 v[110:113], v[66:67], off
	s_waitcnt lgkmcnt(3)
	v_mfma_f32_32x32x16_bf16 v[18:33], v[62:65], v[54:57], v[18:33]
	v_pk_add_f32 v[194:195], v[194:195], v[196:197]
	v_pk_add_f32 v[198:199], v[198:199], v[200:201]
	v_pk_add_f32 v[202:203], v[202:203], v[204:205]
	v_pk_add_f32 v[206:207], v[206:207], v[208:209]
	v_pk_add_f32 v[210:211], v[210:211], v[212:213]
	v_pk_add_f32 v[214:215], v[214:215], v[218:219]
	v_pk_add_f32 v[220:221], v[220:221], v[222:223]
	v_add_f32_e32 v189, v189, v216
	s_waitcnt lgkmcnt(1)
	v_mfma_f32_32x32x16_bf16 v[18:33], v[78:81], v[50:53], v[18:33]
	v_pk_add_f32 v[194:195], v[194:195], v[198:199]
	v_pk_add_f32 v[202:203], v[202:203], v[206:207]
	v_pk_add_f32 v[210:211], v[210:211], v[214:215]
	v_pk_add_f32 v[220:221], v[220:221], v[224:225]
	v_mfma_f32_32x32x16_bf16 v[18:33], v[74:77], v[58:61], v[18:33]
	v_pk_add_f32 v[194:195], v[194:195], v[202:203]
	v_pk_add_f32 v[210:211], v[210:211], v[220:221]
	s_waitcnt lgkmcnt(0)
	v_mfma_f32_32x32x16_bf16 v[18:33], v[190:193], v[70:73], v[18:33]
	v_pk_add_f32 v[194:195], v[194:195], v[210:211]
	v_add_f32_e32 v189, v189, v194
	v_add_f32_e32 v189, v189, v195
	v_add_f32_e32 v187, v187, v189
	s_waitcnt lgkmcnt(0)
	s_barrier
	s_cmp_lt_i32 s33, 7
	v_add_u32_e32 v188, 0xffffff00, v188
	s_cbranch_scc0 .LBB0_217
	s_mov_b32 s33, s70
	s_branch .LBB0_255

; #define LAS __attribute__((address_space(3)))
; #define MFMA32(a, b, c) __builtin_amdgcn_mfma_f32_32x32x16_bf16((a), (b), (c), 0, 0, 0)
; __device__ __forceinline__ void attn_item(const bf16_t* __restrict__ Q, const bf16_t* __restrict__ Kb, const bf16_t* __restrict__ VT, const bf16_t* __restrict__ GA, ...
;     ...
;         for (int d0 = 1; d0 < 4; ++d0) {
;             const bf16x8 k0 = *(const LAS bf16x8*)(kfp + d0 * 32), k1 = *(const LAS bf16x8*)(kfp + 32 * ATP + d0 * 32);
;             s0 = MFMA32(k0, qf[d0], s0); s1 = MFMA32(k1, qf[d0], s1);
;         }
;         float tmax = fmaxf(s0[0], s1[0]);
; #pragma unroll
;         for (int i = 1; i < 16; ++i) tmax = fmaxf(tmax, fmaxf(s0[i], s1[i]));
;         tmax = fmaxf(tmax, __shfl_xor(tmax, 32));
;         if (j == jmin || __any(tmax > ATT_THR)) {
;             const float dl = (j == jmin) ? tmax : fmaxf(tmax, 0.f);
;             mref += dl;
;             const float alpha = (j == jmin) ? 1.f : __builtin_amdgcn_exp2f(-dl);
;             lrun *= alpha;
; #pragma unroll
;             for (int i = 0; i < 16; ++i) { s0[i] -= dl; s1[i] -= dl; o0[i] *= alpha; o1[i] *= alpha; cinit[i] = cfar - mref; }
.Latt1_qkrest:
	s_waitcnt lgkmcnt(5)
	v_mfma_f32_32x32x16_bf16 v[50:65], v[198:201], v[86:89], v[50:65]
	s_waitcnt lgkmcnt(4)
	v_mfma_f32_32x32x16_bf16 v[66:81], v[202:205], v[86:89], v[66:81]
	s_waitcnt lgkmcnt(3)
	v_mfma_f32_32x32x16_bf16 v[50:65], v[206:209], v[90:93], v[50:65]
	s_waitcnt lgkmcnt(2)
	v_mfma_f32_32x32x16_bf16 v[66:81], v[210:213], v[90:93], v[66:81]
	s_waitcnt lgkmcnt(1)
	v_mfma_f32_32x32x16_bf16 v[66:81], v[218:221], v[94:97], v[66:81]
	s_waitcnt lgkmcnt(0)
	v_mfma_f32_32x32x16_bf16 v[50:65], v[222:225], v[94:97], v[50:65]
	s_nop 9
	v_max3_f32 v189, v66, v67, v68
	v_max3_f32 v190, v69, v70, v71
	v_max3_f32 v191, v72, v73, v74
	v_max3_f32 v192, v75, v76, v77
	v_max3_f32 v193, v78, v79, v80
	v_max3_f32 v194, v81, v50, v51
	v_max3_f32 v195, v52, v53, v54
	v_max3_f32 v196, v55, v56, v57
	v_max3_f32 v197, v58, v59, v60
	v_max3_f32 v198, v61, v62, v63
	v_max3_f32 v199, v64, v65, v189
	v_max3_f32 v190, v190, v191, v192
	v_max3_f32 v193, v193, v194, v195
	v_max3_f32 v196, v196, v197, v198
	v_max3_f32 v189, v199, v190, v193
	v_max_f32_e32 v189, v189, v196
	ds_bpermute_b32 v190, v1, v189
	s_waitcnt lgkmcnt(0)
	v_max_f32_e32 v190, v190, v190
	v_max_f32_e32 v189, v189, v190
	v_cmp_lt_f32_e32 vcc, s33, v189
	s_cbranch_vccz .LBB0_685
	v_max_f32_e32 v34, v189, v189
	v_max_f32_e32 v36, 0, v34
	v_exp_f32_e64 v38, -v36
	v_add_f32_e32 v132, v132, v36
	v_sub_f32_e32 v34, v0, v132
	v_pk_add_f32 v[50:51], v[50:51], v[36:37] op_sel_hi:[1,0] neg_lo:[0,1] neg_hi:[0,1]
	v_pk_add_f32 v[66:67], v[66:67], v[36:37] op_sel_hi:[1,0] neg_lo:[0,1] neg_hi:[0,1]
	v_pk_add_f32 v[52:53], v[52:53], v[36:37] op_sel_hi:[1,0] neg_lo:[0,1] neg_hi:[0,1]
	v_pk_add_f32 v[68:69], v[68:69], v[36:37] op_sel_hi:[1,0] neg_lo:[0,1] neg_hi:[0,1]
	v_pk_add_f32 v[54:55], v[54:55], v[36:37] op_sel_hi:[1,0] neg_lo:[0,1] neg_hi:[0,1]
	v_pk_add_f32 v[70:71], v[70:71], v[36:37] op_sel_hi:[1,0] neg_lo:[0,1] neg_hi:[0,1]
	v_pk_add_f32 v[56:57], v[56:57], v[36:37] op_sel_hi:[1,0] neg_lo:[0,1] neg_hi:[0,1]
	v_pk_add_f32 v[72:73], v[72:73], v[36:37] op_sel_hi:[1,0] neg_lo:[0,1] neg_hi:[0,1]
	v_pk_add_f32 v[58:59], v[58:59], v[36:37] op_sel_hi:[1,0] neg_lo:[0,1] neg_hi:[0,1]
	v_pk_add_f32 v[74:75], v[74:75], v[36:37] op_sel_hi:[1,0] neg_lo:[0,1] neg_hi:[0,1]
	v_pk_add_f32 v[60:61], v[60:61], v[36:37] op_sel_hi:[1,0] neg_lo:[0,1] neg_hi:[0,1]
	v_pk_add_f32 v[76:77], v[76:77], v[36:37] op_sel_hi:[1,0] neg_lo:[0,1] neg_hi:[0,1]
	v_pk_add_f32 v[62:63], v[62:63], v[36:37] op_sel_hi:[1,0] neg_lo:[0,1] neg_hi:[0,1]
	v_pk_add_f32 v[78:79], v[78:79], v[36:37] op_sel_hi:[1,0] neg_lo:[0,1] neg_hi:[0,1]
	v_pk_add_f32 v[64:65], v[64:65], v[36:37] op_sel_hi:[1,0] neg_lo:[0,1] neg_hi:[0,1]
	v_pk_add_f32 v[80:81], v[80:81], v[36:37] op_sel_hi:[1,0] neg_lo:[0,1] neg_hi:[0,1]
	v_pk_mul_f32 v[16:17], v[16:17], v[38:39] op_sel_hi:[1,0]
	v_pk_mul_f32 v[14:15], v[14:15], v[38:39] op_sel_hi:[1,0]
	v_pk_mul_f32 v[12:13], v[12:13], v[38:39] op_sel_hi:[1,0]
	v_pk_mul_f32 v[10:11], v[10:11], v[38:39] op_sel_hi:[1,0]
	v_pk_mul_f32 v[8:9], v[8:9], v[38:39] op_sel_hi:[1,0]
	v_pk_mul_f32 v[6:7], v[6:7], v[38:39] op_sel_hi:[1,0]
	v_pk_mul_f32 v[4:5], v[4:5], v[38:39] op_sel_hi:[1,0]
	v_pk_mul_f32 v[2:3], v[2:3], v[38:39] op_sel_hi:[1,0]
	v_pk_mul_f32 v[32:33], v[32:33], v[38:39] op_sel_hi:[1,0]
	v_pk_mul_f32 v[30:31], v[30:31], v[38:39] op_sel_hi:[1,0]
	v_pk_mul_f32 v[28:29], v[28:29], v[38:39] op_sel_hi:[1,0]
	v_pk_mul_f32 v[26:27], v[26:27], v[38:39] op_sel_hi:[1,0]
	v_pk_mul_f32 v[24:25], v[24:25], v[38:39] op_sel_hi:[1,0]
	v_pk_mul_f32 v[22:23], v[22:23], v[38:39] op_sel_hi:[1,0]
	v_pk_mul_f32 v[20:21], v[20:21], v[38:39] op_sel_hi:[1,0]
	v_pk_mul_f32 v[18:19], v[18:19], v[38:39] op_sel_hi:[1,0]
	v_mul_f32_e32 v187, v187, v38
	v_mov_b32_e32 v35, v34
	v_mov_b32_e32 v36, v34
	v_mov_b32_e32 v37, v34
	v_mov_b32_e32 v38, v34
	v_mov_b32_e32 v39, v34
	v_mov_b32_e32 v40, v34
	v_mov_b32_e32 v41, v34
	v_mov_b32_e32 v42, v34
	v_mov_b32_e32 v43, v34
	v_mov_b32_e32 v44, v34
	v_mov_b32_e32 v45, v34
	v_mov_b32_e32 v46, v34
	v_mov_b32_e32 v47, v34
	v_mov_b32_e32 v48, v34
	v_mov_b32_e32 v49, v34
; #define LAS __attribute__((address_space(3)))
; __device__ __forceinline__ unsigned pk2(float lo, float hi) { f32x2 v = {lo, hi}; bf16x2_t b = __builtin_convertvector(v, bf16x2_t); return __builtin_bit_cast(unsigned, b); }
; #define MFMA32(a, b, c) __builtin_amdgcn_mfma_f32_32x32x16_bf16((a), (b), (c), 0, 0, 0)
; #define ATT_BAR() asm volatile("s_waitcnt lgkmcnt(0)\n\ts_barrier" ::: "memory")
; __device__ __forceinline__ void attn_item(const bf16_t* __restrict__ Q, const bf16_t* __restrict__ Kb, const bf16_t* __restrict__ VT, const bf16_t* __restrict__ GA, ...
;     ...
;         float ls = 0.f;
; #pragma unroll
;         for (int i = 0; i < 16; ++i) { s0[i] = __builtin_amdgcn_exp2f(s0[i]); s1[i] = __builtin_amdgcn_exp2f(s1[i]); ls += s0[i] + s1[i]; }
;         lrun += ls;
; #pragma unroll
;         for (int s = 0; s < 2; ++s) {
;             u32x4 pa, pb;
;             pa.x = pk2(s0[8 * s + 0], s0[8 * s + 1]); pa.y = pk2(s0[8 * s + 2], s0[8 * s + 3]); pa.z = pk2(s0[8 * s + 4], s0[8 * s + 5]); pa.w = pk2(s0[8 * s + 6], s0[8 * s + 7]);
;             pb.x = pk2(s1[8 * s + 0], s1[8 * s + 1]); pb.y = pk2(s1[8 * s + 2], s1[8 * s + 3]); pb.z = pk2(s1[8 * s + 4], s1[8 * s + 5]); pb.w = pk2(s1[8 * s + 6], s1[8 * s + 7]);
;             const bf16x8 va0 = *(const LAS bf16x8*)(vfp + 32 * s), va1 = *(const LAS bf16x8*)(vfp + 32 * ATP + 32 * s);
;             const bf16x8 vb0 = *(const LAS bf16x8*)(vfp + 64 + 32 * s), vb1 = *(const LAS bf16x8*)(vfp + 32 * ATP + 64 + 32 * s);
;             o0 = MFMA32(va0, __builtin_bit_cast(bf16x8, pa), o0); o1 = MFMA32(va1, __builtin_bit_cast(bf16x8, pa), o1);
;             o0 = MFMA32(vb0, __builtin_bit_cast(bf16x8, pb), o0); o1 = MFMA32(vb1, __builtin_bit_cast(bf16x8, pb), o1);
;         }
;         buf ^= 1;
; #pragma unroll
;         for (int i = 0; i < 8; ++i) *(LAS u32x4*)(pl + buf * ATT_WAVE_LDS + stoff + 8 * i * ATP) = tr[i];
;         tg += (j + 2 <= 8) ? tstep : (size_t)0;
; #pragma unroll
;         for (int i = 0; i < 8; ++i) tr[i] = *(const u32x4*)(tg + i * rstep);
;         ATT_BAR();
.LBB0_685:
	v_add3_u32 v190, s28, v165, v167
	s_xor_b32 s72, s72, 1
	s_mul_i32 s99, s72, 0x4800
	v_add_u32_e32 v226, s99, v186
	v_exp_f32_e32 v189, v50
	v_exp_f32_e32 v220, v51
	v_exp_f32_e32 v222, v52
	v_exp_f32_e32 v224, v53
	ds_read_b128 v[50:53], v190 offset:9216
	s_waitcnt vmcnt(1)
	ds_write_b128 v226, v[126:129]
	ds_write_b128 v226, v[122:125] offset:1152
	ds_write_b128 v226, v[106:109] offset:2304
	ds_write_b128 v226, v[118:121] offset:3456
	ds_write_b128 v226, v[102:105] offset:4608
	ds_write_b128 v226, v[114:117] offset:5760
	ds_write_b128 v226, v[98:101] offset:6912
	s_waitcnt vmcnt(0)
	ds_write_b128 v226, v[110:113] offset:8064
	v_exp_f32_e32 v195, v54
	v_exp_f32_e32 v194, v55
	v_exp_f32_e32 v199, v56
	v_exp_f32_e32 v198, v57
	v_exp_f32_e32 v203, v58
	v_exp_f32_e32 v202, v59
	v_cvt_pk_bf16_f32 v54, v189, v220
	v_cvt_pk_bf16_f32 v55, v222, v224
	v_cvt_pk_bf16_f32 v56, v195, v194
	v_cvt_pk_bf16_f32 v57, v199, v198
	v_exp_f32_e32 v197, v70
	v_exp_f32_e32 v196, v71
	s_waitcnt lgkmcnt(8)
	v_mfma_f32_32x32x16_bf16 v[2:17], v[50:53], v[54:57], v[2:17]
	v_exp_f32_e32 v201, v72
	v_exp_f32_e32 v200, v73
	v_exp_f32_e32 v216, v66
	v_exp_f32_e32 v221, v67
	v_exp_f32_e32 v223, v68
	v_exp_f32_e32 v225, v69
	v_exp_f32_e32 v207, v60
	v_exp_f32_e32 v206, v61
	v_exp_f32_e32 v211, v62
	v_exp_f32_e32 v210, v63
	v_exp_f32_e32 v215, v64
	v_exp_f32_e32 v214, v65
	ds_read_b128 v[58:61], v190 offset:9280
	ds_read_b128 v[62:65], v190 offset:9248
	v_cvt_pk_bf16_f32 v50, v216, v221
	v_cvt_pk_bf16_f32 v51, v223, v225
	v_cvt_pk_bf16_f32 v52, v197, v196
	v_cvt_pk_bf16_f32 v53, v201, v200
	ds_read_b128 v[66:69], v190 offset:9312
	s_waitcnt lgkmcnt(2)
	v_mfma_f32_32x32x16_bf16 v[2:17], v[58:61], v[50:53], v[2:17]
	v_cvt_pk_bf16_f32 v58, v203, v202
	v_cvt_pk_bf16_f32 v59, v207, v206
	v_exp_f32_e32 v205, v74
	v_cvt_pk_bf16_f32 v60, v211, v210
	v_cvt_pk_bf16_f32 v61, v215, v214
	v_exp_f32_e32 v204, v75
	v_exp_f32_e32 v209, v76
	s_waitcnt lgkmcnt(1)
	v_mfma_f32_32x32x16_bf16 v[2:17], v[62:65], v[58:61], v[2:17]
	v_exp_f32_e32 v208, v77
	v_exp_f32_e32 v213, v78
	v_exp_f32_e32 v212, v79
	v_exp_f32_e32 v219, v80
	v_exp_f32_e32 v218, v81
	s_add_i32 s70, s84, 1
	v_cvt_pk_bf16_f32 v70, v205, v204
	v_cvt_pk_bf16_f32 v71, v209, v208
	v_cvt_pk_bf16_f32 v72, v213, v212
	v_cvt_pk_bf16_f32 v73, v219, v218
	s_cmp_lt_i32 s84, 6
	s_waitcnt lgkmcnt(0)
	v_mfma_f32_32x32x16_bf16 v[2:17], v[66:69], v[70:73], v[2:17]
	s_cselect_b32 s7, s64, 0
	s_lshl_b32 s28, s7, 1
	v_lshl_add_u64 v[152:153], v[152:153], 0, s[28:29]
	s_mov_b32 s67, s29
	ds_read_b128 v[62:65], v190 offset:13824
	ds_read_b128 v[74:77], v190 offset:13856
	ds_read_b128 v[78:81], v190 offset:13888
	ds_read_b128 v[190:193], v190 offset:13920
	v_lshl_add_u64 v[66:67], v[152:153], 0, s[66:67]
	v_lshl_add_u64 v[68:69], v[66:67], 0, s[68:69]
	global_load_dwordx4 v[122:125], v[66:67], off
	global_load_dwordx4 v[106:109], v[68:69], off
	v_lshl_add_u64 v[66:67], v[68:69], 0, s[68:69]
	v_lshl_add_u64 v[68:69], v[66:67], 0, s[68:69]
	global_load_dwordx4 v[118:121], v[66:67], off
	global_load_dwordx4 v[102:105], v[68:69], off
	v_lshl_add_u64 v[66:67], v[68:69], 0, s[68:69]
	v_lshl_add_u64 v[68:69], v[66:67], 0, s[68:69]
	global_load_dwordx4 v[114:117], v[66:67], off
	global_load_dwordx4 v[98:101], v[68:69], off
	v_lshl_add_u64 v[66:67], v[68:69], 0, s[68:69]
	global_load_dwordx4 v[126:129], v[152:153], off
	global_load_dwordx4 v[110:113], v[66:67], off
	s_waitcnt lgkmcnt(3)
	v_mfma_f32_32x32x16_bf16 v[18:33], v[62:65], v[54:57], v[18:33]
	v_pk_add_f32 v[194:195], v[194:195], v[196:197]
	v_pk_add_f32 v[198:199], v[198:199], v[200:201]
	v_pk_add_f32 v[202:203], v[202:203], v[204:205]
	v_pk_add_f32 v[206:207], v[206:207], v[208:209]
	v_pk_add_f32 v[210:211], v[210:211], v[212:213]
	v_pk_add_f32 v[214:215], v[214:215], v[218:219]
	v_pk_add_f32 v[220:221], v[220:221], v[222:223]
	v_add_f32_e32 v189, v189, v216
	s_waitcnt lgkmcnt(1)
	v_mfma_f32_32x32x16_bf16 v[18:33], v[78:81], v[50:53], v[18:33]
	v_pk_add_f32 v[194:195], v[194:195], v[198:199]
	v_pk_add_f32 v[202:203], v[202:203], v[206:207]
	v_pk_add_f32 v[210:211], v[210:211], v[214:215]
	v_pk_add_f32 v[220:221], v[220:221], v[224:225]
	v_mfma_f32_32x32x16_bf16 v[18:33], v[74:77], v[58:61], v[18:33]
	v_pk_add_f32 v[194:195], v[194:195], v[202:203]
	v_pk_add_f32 v[210:211], v[210:211], v[220:221]
	s_waitcnt lgkmcnt(0)
	v_mfma_f32_32x32x16_bf16 v[18:33], v[190:193], v[70:73], v[18:33]
	v_pk_add_f32 v[194:195], v[194:195], v[210:211]
	v_add_f32_e32 v189, v189, v194
	v_add_f32_e32 v189, v189, v195
	v_add_f32_e32 v187, v187, v189
	s_waitcnt lgkmcnt(0)
	s_barrier
	s_cmp_lt_i32 s84, 7
	v_add_u32_e32 v188, 0xffffff00, v188
	s_cbranch_scc0 .LBB0_641
	s_mov_b32 s84, s70
	s_branch .LBB0_679
